# no L2 write-back after the deferred in-proj tiles in XCD-local mode (their only readers run on the same XCD)
# speedup vs baseline: 1.0020x; 1.0020x over previous
.LBB0_1829:
	s_add_u32 s8, s6, 0xae00000
	s_addc_u32 s9, s7, 0
	s_add_u32 s0, s6, 0x600000
	s_addc_u32 s1, s7, 0
	s_mul_hi_i32 s10, s45, 0x18c00
	s_mul_i32 s45, s45, 0x18c00
	s_add_u32 s6, s6, s45
	s_addc_u32 s7, s7, s10
	s_lshl_b32 s10, s86, 8
	v_lshl_add_u32 v44, v147, 3, s22
	v_add_u32_e32 v150, 0x800, v44
	s_add_i32 s17, s17, s10
	v_ashrrev_i32_e32 v151, 31, v150
	v_add_u32_e32 v148, s17, v146
	v_lshl_add_u64 v[44:45], v[150:151], 2, s[6:7]
	s_mov_b64 s[6:7], 0x300000
	v_lshlrev_b32_e32 v146, 2, v147
	v_ashrrev_i32_e32 v149, 31, v148
	v_lshl_add_u64 v[48:49], v[44:45], 0, s[6:7]
	s_mov_b32 s6, 0x300000
	v_ashrrev_i32_e32 v147, 31, v146
	v_lshlrev_b64 v[152:153], 6, v[148:149]
	v_add_co_u32_e32 v44, vcc, s6, v44
	v_lshl_add_u64 v[152:153], s[0:1], 0, v[152:153]
	v_lshlrev_b64 v[146:147], 2, v[146:147]
	v_addc_co_u32_e32 v45, vcc, 0, v45, vcc
	v_lshl_add_u64 v[152:153], v[152:153], 0, v[146:147]
	global_load_dwordx4 v[60:63], v[44:45], off
	global_load_dwordx4 v[56:59], v[48:49], off offset:16
	s_nop 0
	global_load_dwordx4 v[44:47], v[48:49], off offset:528
	s_nop 0
	global_load_dwordx4 v[48:51], v[48:49], off offset:512
	s_nop 0
	global_load_dwordx4 v[152:155], v[152:153], off
	s_waitcnt vmcnt(0)
	v_add_f32_e32 v64, v152, v153
	v_add_f32_e32 v149, v154, v155
	v_add_f32_e32 v64, v64, v149
	v_mov_b32_e32 v149, v64
	s_nop 1
	v_permlane16_swap_b32_e32 v64, v149
	v_add_f32_e32 v64, v64, v149
	v_mov_b32_e32 v149, v64
	s_nop 1
	v_permlane32_swap_b32_e32 v64, v149
	v_add_f32_e32 v64, v64, v149
	v_fmamk_f32 v64, v64, 0x3a800000, v229
	v_cmp_gt_f32_e32 vcc, s55, v64
	v_mul_f32_e32 v149, 0x4b800000, v64
	s_nop 0
	v_cndmask_b32_e32 v64, v64, v149, vcc
	v_rsq_f32_e32 v64, v64
	s_nop 0
	v_mul_f32_e32 v149, 0x45800000, v64
	v_cndmask_b32_e32 v64, v64, v149, vcc
	v_pk_fma_f32 v[144:145], v[144:145], v[64:65], v[62:63] op_sel_hi:[1,0,1]
	v_pk_fma_f32 v[142:143], v[142:143], v[64:65], v[60:61] op_sel_hi:[1,0,1]
	v_pk_fma_f32 v[138:139], v[138:139], v[64:65], v[56:57] op_sel_hi:[1,0,1]
	v_pk_fma_f32 v[140:141], v[140:141], v[64:65], v[58:59] op_sel_hi:[1,0,1]
	v_cvt_pk_bf16_f32 v142, v142, v143
	v_cvt_pk_bf16_f32 v143, v144, v145
	v_cvt_pk_bf16_f32 v144, v138, v139
	v_mov_b64_e32 v[138:139], s[8:9]
	v_cvt_pk_bf16_f32 v145, v140, v141
	v_mad_i64_i32 v[152:153], s[6:7], v148, s93, v[138:139]
	v_lshlrev_b64 v[140:141], 1, v[150:151]
	v_lshl_add_u64 v[150:151], v[152:153], 0, v[140:141]
	v_pk_fma_f32 v[134:135], v[134:135], v[64:65], v[48:49] op_sel_hi:[1,0,1]
	global_store_dwordx4 v[150:151], v[142:145], off
	v_pk_fma_f32 v[136:137], v[136:137], v[64:65], v[50:51] op_sel_hi:[1,0,1]
	s_nop 0
	v_pk_fma_f32 v[142:143], v[132:133], v[64:65], v[46:47] op_sel_hi:[1,0,1]
	v_pk_fma_f32 v[132:133], v[130:131], v[64:65], v[44:45] op_sel_hi:[1,0,1]
	v_cvt_pk_bf16_f32 v130, v134, v135
	v_add_u32_e32 v134, 16, v148
	v_cvt_pk_bf16_f32 v131, v136, v137
	v_cvt_pk_bf16_f32 v132, v132, v133
	v_cvt_pk_bf16_f32 v133, v142, v143
	v_ashrrev_i32_e32 v135, 31, v134
	global_store_dwordx4 v[150:151], v[130:133], off offset:256
	s_nop 1
	v_lshlrev_b64 v[130:131], 6, v[134:135]
	v_lshl_add_u64 v[130:131], s[0:1], 0, v[130:131]
	v_lshl_add_u64 v[130:131], v[130:131], 0, v[146:147]
	global_load_dwordx4 v[130:133], v[130:131], off
	s_waitcnt vmcnt(0)
	v_add_f32_e32 v64, v130, v131
	v_add_f32_e32 v130, v132, v133
	v_add_f32_e32 v64, v64, v130
	v_mov_b32_e32 v130, v64
	s_nop 1
	v_permlane16_swap_b32_e32 v64, v130
	v_add_f32_e32 v64, v64, v130
	v_mov_b32_e32 v130, v64
	s_nop 1
	v_permlane32_swap_b32_e32 v64, v130
	v_add_f32_e32 v64, v64, v130
	v_fmamk_f32 v64, v64, 0x3a800000, v229
	v_cmp_gt_f32_e32 vcc, s55, v64
	v_mul_f32_e32 v130, 0x4b800000, v64
	s_nop 0
	v_cndmask_b32_e32 v64, v64, v130, vcc
	v_rsq_f32_e32 v64, v64
	s_nop 0
	v_mul_f32_e32 v130, 0x45800000, v64
	v_cndmask_b32_e32 v64, v64, v130, vcc
	v_pk_fma_f32 v[126:127], v[126:127], v[64:65], v[60:61] op_sel_hi:[1,0,1]
	v_pk_fma_f32 v[128:129], v[128:129], v[64:65], v[62:63] op_sel_hi:[1,0,1]
	v_pk_fma_f32 v[130:131], v[124:125], v[64:65], v[58:59] op_sel_hi:[1,0,1]
	v_pk_fma_f32 v[124:125], v[122:123], v[64:65], v[56:57] op_sel_hi:[1,0,1]
	v_cvt_pk_bf16_f32 v122, v126, v127
	v_mad_i64_i32 v[126:127], s[6:7], v134, s93, v[138:139]
	v_cvt_pk_bf16_f32 v123, v128, v129
	v_cvt_pk_bf16_f32 v124, v124, v125
	v_cvt_pk_bf16_f32 v125, v130, v131
	v_lshl_add_u64 v[126:127], v[126:127], 0, v[140:141]
	v_pk_fma_f32 v[118:119], v[118:119], v[64:65], v[48:49] op_sel_hi:[1,0,1]
	global_store_dwordx4 v[126:127], v[122:125], off
	v_pk_fma_f32 v[120:121], v[120:121], v[64:65], v[50:51] op_sel_hi:[1,0,1]
	s_nop 0
	v_pk_fma_f32 v[122:123], v[116:117], v[64:65], v[46:47] op_sel_hi:[1,0,1]
	v_pk_fma_f32 v[116:117], v[114:115], v[64:65], v[44:45] op_sel_hi:[1,0,1]
	v_cvt_pk_bf16_f32 v114, v118, v119
	v_add_u32_e32 v118, 32, v148
	v_cvt_pk_bf16_f32 v115, v120, v121
	v_cvt_pk_bf16_f32 v116, v116, v117
	v_cvt_pk_bf16_f32 v117, v122, v123
	v_ashrrev_i32_e32 v119, 31, v118
	global_store_dwordx4 v[126:127], v[114:117], off offset:256
	s_nop 1
	v_lshlrev_b64 v[114:115], 6, v[118:119]
	v_lshl_add_u64 v[114:115], s[0:1], 0, v[114:115]
	v_lshl_add_u64 v[114:115], v[114:115], 0, v[146:147]
	global_load_dwordx4 v[114:117], v[114:115], off
	s_waitcnt vmcnt(0)
	v_add_f32_e32 v64, v114, v115
	v_add_f32_e32 v114, v116, v117
	v_add_f32_e32 v64, v64, v114
	v_mov_b32_e32 v114, v64
	s_nop 1
	v_permlane16_swap_b32_e32 v64, v114
	v_add_f32_e32 v64, v64, v114
	v_mov_b32_e32 v114, v64
	s_nop 1
	v_permlane32_swap_b32_e32 v64, v114
	v_add_f32_e32 v64, v64, v114
	v_fmamk_f32 v64, v64, 0x3a800000, v229
	v_cmp_gt_f32_e32 vcc, s55, v64
	v_mul_f32_e32 v114, 0x4b800000, v64
	s_nop 0
	v_cndmask_b32_e32 v64, v64, v114, vcc
	v_rsq_f32_e32 v64, v64
	s_nop 0
	v_mul_f32_e32 v114, 0x45800000, v64
	v_cndmask_b32_e32 v64, v64, v114, vcc
	v_pk_fma_f32 v[110:111], v[110:111], v[64:65], v[60:61] op_sel_hi:[1,0,1]
	v_pk_fma_f32 v[112:113], v[112:113], v[64:65], v[62:63] op_sel_hi:[1,0,1]
	v_pk_fma_f32 v[114:115], v[108:109], v[64:65], v[58:59] op_sel_hi:[1,0,1]
	v_pk_fma_f32 v[108:109], v[106:107], v[64:65], v[56:57] op_sel_hi:[1,0,1]
	v_cvt_pk_bf16_f32 v106, v110, v111
	v_mad_i64_i32 v[110:111], s[6:7], v118, s93, v[138:139]
	v_cvt_pk_bf16_f32 v107, v112, v113
	v_cvt_pk_bf16_f32 v108, v108, v109
	v_cvt_pk_bf16_f32 v109, v114, v115
	v_lshl_add_u64 v[110:111], v[110:111], 0, v[140:141]
	v_pk_fma_f32 v[102:103], v[102:103], v[64:65], v[48:49] op_sel_hi:[1,0,1]
	global_store_dwordx4 v[110:111], v[106:109], off
	v_pk_fma_f32 v[104:105], v[104:105], v[64:65], v[50:51] op_sel_hi:[1,0,1]
	s_nop 0
	v_pk_fma_f32 v[106:107], v[100:101], v[64:65], v[46:47] op_sel_hi:[1,0,1]
	v_pk_fma_f32 v[100:101], v[98:99], v[64:65], v[44:45] op_sel_hi:[1,0,1]
	v_cvt_pk_bf16_f32 v98, v102, v103
	v_add_u32_e32 v102, 48, v148
	v_cvt_pk_bf16_f32 v99, v104, v105
	v_cvt_pk_bf16_f32 v100, v100, v101
	v_cvt_pk_bf16_f32 v101, v106, v107
	v_ashrrev_i32_e32 v103, 31, v102
	global_store_dwordx4 v[110:111], v[98:101], off offset:256
	s_nop 1
	v_lshlrev_b64 v[98:99], 6, v[102:103]
	v_lshl_add_u64 v[98:99], s[0:1], 0, v[98:99]
	v_lshl_add_u64 v[98:99], v[98:99], 0, v[146:147]
	global_load_dwordx4 v[98:101], v[98:99], off
	s_waitcnt vmcnt(0)
	v_add_f32_e32 v64, v98, v99
	v_add_f32_e32 v98, v100, v101
	v_add_f32_e32 v64, v64, v98
	v_mov_b32_e32 v98, v64
	s_nop 1
	v_permlane16_swap_b32_e32 v64, v98
	v_add_f32_e32 v64, v64, v98
	v_mov_b32_e32 v98, v64
	s_nop 1
	v_permlane32_swap_b32_e32 v64, v98
	v_add_f32_e32 v64, v64, v98
	v_fmamk_f32 v64, v64, 0x3a800000, v229
	v_cmp_gt_f32_e32 vcc, s55, v64
	v_mul_f32_e32 v98, 0x4b800000, v64
	s_nop 0
	v_cndmask_b32_e32 v64, v64, v98, vcc
	v_rsq_f32_e32 v64, v64
	s_nop 0
	v_mul_f32_e32 v98, 0x45800000, v64
	v_cndmask_b32_e32 v64, v64, v98, vcc
	v_pk_fma_f32 v[94:95], v[94:95], v[64:65], v[60:61] op_sel_hi:[1,0,1]
	v_pk_fma_f32 v[96:97], v[96:97], v[64:65], v[62:63] op_sel_hi:[1,0,1]
	v_pk_fma_f32 v[98:99], v[92:93], v[64:65], v[58:59] op_sel_hi:[1,0,1]
	v_pk_fma_f32 v[92:93], v[90:91], v[64:65], v[56:57] op_sel_hi:[1,0,1]
	v_cvt_pk_bf16_f32 v90, v94, v95
	v_mad_i64_i32 v[94:95], s[6:7], v102, s93, v[138:139]
	v_cvt_pk_bf16_f32 v91, v96, v97
	v_cvt_pk_bf16_f32 v92, v92, v93
	v_cvt_pk_bf16_f32 v93, v98, v99
	v_lshl_add_u64 v[94:95], v[94:95], 0, v[140:141]
	v_pk_fma_f32 v[86:87], v[86:87], v[64:65], v[48:49] op_sel_hi:[1,0,1]
	global_store_dwordx4 v[94:95], v[90:93], off
	v_pk_fma_f32 v[88:89], v[88:89], v[64:65], v[50:51] op_sel_hi:[1,0,1]
	s_nop 0
	v_pk_fma_f32 v[90:91], v[84:85], v[64:65], v[46:47] op_sel_hi:[1,0,1]
	v_pk_fma_f32 v[84:85], v[82:83], v[64:65], v[44:45] op_sel_hi:[1,0,1]
	v_cvt_pk_bf16_f32 v82, v86, v87
	v_add_u32_e32 v86, 0x80, v148
	v_cvt_pk_bf16_f32 v83, v88, v89
	v_cvt_pk_bf16_f32 v84, v84, v85
	v_cvt_pk_bf16_f32 v85, v90, v91
	v_ashrrev_i32_e32 v87, 31, v86
	global_store_dwordx4 v[94:95], v[82:85], off offset:256
	s_nop 1
	v_lshlrev_b64 v[82:83], 6, v[86:87]
	v_lshl_add_u64 v[82:83], s[0:1], 0, v[82:83]
	v_lshl_add_u64 v[82:83], v[82:83], 0, v[146:147]
	global_load_dwordx4 v[82:85], v[82:83], off
	s_waitcnt vmcnt(0)
	v_add_f32_e32 v64, v82, v83
	v_add_f32_e32 v82, v84, v85
	v_add_f32_e32 v64, v64, v82
	v_mov_b32_e32 v82, v64
	s_nop 1
	v_permlane16_swap_b32_e32 v64, v82
	v_add_f32_e32 v64, v64, v82
	v_mov_b32_e32 v82, v64
	s_nop 1
	v_permlane32_swap_b32_e32 v64, v82
	v_add_f32_e32 v64, v64, v82
	v_fmamk_f32 v64, v64, 0x3a800000, v229
	v_cmp_gt_f32_e32 vcc, s55, v64
	v_mul_f32_e32 v82, 0x4b800000, v64
	s_nop 0
	v_cndmask_b32_e32 v64, v64, v82, vcc
	v_rsq_f32_e32 v64, v64
	s_nop 0
	v_mul_f32_e32 v82, 0x45800000, v64
	v_cndmask_b32_e32 v64, v64, v82, vcc
	v_pk_fma_f32 v[78:79], v[78:79], v[64:65], v[60:61] op_sel_hi:[1,0,1]
	v_pk_fma_f32 v[80:81], v[80:81], v[64:65], v[62:63] op_sel_hi:[1,0,1]
	v_pk_fma_f32 v[82:83], v[76:77], v[64:65], v[58:59] op_sel_hi:[1,0,1]
	v_pk_fma_f32 v[76:77], v[74:75], v[64:65], v[56:57] op_sel_hi:[1,0,1]
	v_cvt_pk_bf16_f32 v74, v78, v79
	v_mad_i64_i32 v[78:79], s[6:7], v86, s93, v[138:139]
	v_cvt_pk_bf16_f32 v75, v80, v81
	v_cvt_pk_bf16_f32 v76, v76, v77
	v_cvt_pk_bf16_f32 v77, v82, v83
	v_lshl_add_u64 v[78:79], v[78:79], 0, v[140:141]
	v_pk_fma_f32 v[70:71], v[70:71], v[64:65], v[48:49] op_sel_hi:[1,0,1]
	global_store_dwordx4 v[78:79], v[74:77], off
	v_pk_fma_f32 v[72:73], v[72:73], v[64:65], v[50:51] op_sel_hi:[1,0,1]
	s_nop 0
	v_pk_fma_f32 v[74:75], v[68:69], v[64:65], v[46:47] op_sel_hi:[1,0,1]
	v_pk_fma_f32 v[68:69], v[66:67], v[64:65], v[44:45] op_sel_hi:[1,0,1]
	v_cvt_pk_bf16_f32 v66, v70, v71
	v_add_u32_e32 v70, 0x90, v148
	v_cvt_pk_bf16_f32 v67, v72, v73
	v_cvt_pk_bf16_f32 v68, v68, v69
	v_cvt_pk_bf16_f32 v69, v74, v75
	v_ashrrev_i32_e32 v71, 31, v70
	global_store_dwordx4 v[78:79], v[66:69], off offset:256
	s_nop 1
	v_lshlrev_b64 v[66:67], 6, v[70:71]
	v_lshl_add_u64 v[66:67], s[0:1], 0, v[66:67]
	v_lshl_add_u64 v[66:67], v[66:67], 0, v[146:147]
	global_load_dwordx4 v[66:69], v[66:67], off
	s_waitcnt vmcnt(0)
	v_add_f32_e32 v64, v66, v67
	v_add_f32_e32 v66, v68, v69
	v_add_f32_e32 v64, v64, v66
	v_mov_b32_e32 v66, v64
	s_nop 1
	v_permlane16_swap_b32_e32 v64, v66
	v_add_f32_e32 v64, v64, v66
	v_mov_b32_e32 v66, v64
	s_nop 1
	v_permlane32_swap_b32_e32 v64, v66
	v_add_f32_e32 v64, v64, v66
	v_fmamk_f32 v64, v64, 0x3a800000, v229
	v_cmp_gt_f32_e32 vcc, s55, v64
	v_mul_f32_e32 v66, 0x4b800000, v64
	s_nop 0
	v_cndmask_b32_e32 v64, v64, v66, vcc
	v_rsq_f32_e32 v64, v64
	s_nop 0
	v_mul_f32_e32 v66, 0x45800000, v64
	v_cndmask_b32_e32 v64, v64, v66, vcc
	v_pk_fma_f32 v[52:53], v[52:53], v[64:65], v[60:61] op_sel_hi:[1,0,1]
	v_pk_fma_f32 v[54:55], v[54:55], v[64:65], v[62:63] op_sel_hi:[1,0,1]
	v_pk_fma_f32 v[66:67], v[42:43], v[64:65], v[58:59] op_sel_hi:[1,0,1]
	v_pk_fma_f32 v[42:43], v[40:41], v[64:65], v[56:57] op_sel_hi:[1,0,1]
	v_cvt_pk_bf16_f32 v40, v52, v53
	v_mad_i64_i32 v[52:53], s[6:7], v70, s93, v[138:139]
	v_cvt_pk_bf16_f32 v41, v54, v55
	v_cvt_pk_bf16_f32 v42, v42, v43
	v_cvt_pk_bf16_f32 v43, v66, v67
	v_lshl_add_u64 v[52:53], v[52:53], 0, v[140:141]
	v_pk_fma_f32 v[36:37], v[36:37], v[64:65], v[48:49] op_sel_hi:[1,0,1]
	global_store_dwordx4 v[52:53], v[40:43], off
	v_pk_fma_f32 v[38:39], v[38:39], v[64:65], v[50:51] op_sel_hi:[1,0,1]
	s_nop 0
	v_pk_fma_f32 v[40:41], v[34:35], v[64:65], v[46:47] op_sel_hi:[1,0,1]
	v_pk_fma_f32 v[34:35], v[32:33], v[64:65], v[44:45] op_sel_hi:[1,0,1]
	v_cvt_pk_bf16_f32 v32, v36, v37
	v_add_u32_e32 v36, 0xa0, v148
	v_cvt_pk_bf16_f32 v33, v38, v39
	v_cvt_pk_bf16_f32 v34, v34, v35
	v_cvt_pk_bf16_f32 v35, v40, v41
	v_ashrrev_i32_e32 v37, 31, v36
	global_store_dwordx4 v[52:53], v[32:35], off offset:256
	s_nop 1
	v_lshlrev_b64 v[32:33], 6, v[36:37]
	v_lshl_add_u64 v[32:33], s[0:1], 0, v[32:33]
	v_lshl_add_u64 v[32:33], v[32:33], 0, v[146:147]
	global_load_dwordx4 v[32:35], v[32:33], off
	s_waitcnt vmcnt(0)
	v_add_f32_e32 v32, v32, v33
	v_add_f32_e32 v33, v34, v35
	v_add_f32_e32 v32, v32, v33
	v_mov_b32_e32 v33, v32
	s_nop 1
	v_permlane16_swap_b32_e32 v32, v33
	v_add_f32_e32 v32, v32, v33
	v_mov_b32_e32 v33, v32
	s_nop 1
	v_permlane32_swap_b32_e32 v32, v33
	v_add_f32_e32 v32, v32, v33
	v_fmamk_f32 v32, v32, 0x3a800000, v229
	v_cmp_gt_f32_e32 vcc, s55, v32
	v_mul_f32_e32 v33, 0x4b800000, v32
	s_nop 0
	v_cndmask_b32_e32 v32, v32, v33, vcc
	v_rsq_f32_e32 v32, v32
	s_nop 0
	v_mul_f32_e32 v33, 0x45800000, v32
	v_cndmask_b32_e32 v32, v32, v33, vcc
	v_pk_fma_f32 v[28:29], v[28:29], v[32:33], v[60:61] op_sel_hi:[1,0,1]
	v_pk_fma_f32 v[30:31], v[30:31], v[32:33], v[62:63] op_sel_hi:[1,0,1]
	v_pk_fma_f32 v[34:35], v[26:27], v[32:33], v[58:59] op_sel_hi:[1,0,1]
	v_pk_fma_f32 v[26:27], v[24:25], v[32:33], v[56:57] op_sel_hi:[1,0,1]
	v_cvt_pk_bf16_f32 v24, v28, v29
	v_mad_i64_i32 v[28:29], s[6:7], v36, s93, v[138:139]
	v_cvt_pk_bf16_f32 v25, v30, v31
	v_cvt_pk_bf16_f32 v26, v26, v27
	v_cvt_pk_bf16_f32 v27, v34, v35
	v_lshl_add_u64 v[28:29], v[28:29], 0, v[140:141]
	v_pk_fma_f32 v[20:21], v[20:21], v[32:33], v[48:49] op_sel_hi:[1,0,1]
	global_store_dwordx4 v[28:29], v[24:27], off
	v_pk_fma_f32 v[22:23], v[22:23], v[32:33], v[50:51] op_sel_hi:[1,0,1]
	s_nop 0
	v_pk_fma_f32 v[24:25], v[18:19], v[32:33], v[46:47] op_sel_hi:[1,0,1]
	v_pk_fma_f32 v[18:19], v[16:17], v[32:33], v[44:45] op_sel_hi:[1,0,1]
	v_cvt_pk_bf16_f32 v16, v20, v21
	v_add_u32_e32 v20, 0xb0, v148
	v_cvt_pk_bf16_f32 v17, v22, v23
	v_cvt_pk_bf16_f32 v18, v18, v19
	v_cvt_pk_bf16_f32 v19, v24, v25
	v_ashrrev_i32_e32 v21, 31, v20
	global_store_dwordx4 v[28:29], v[16:19], off offset:256
	s_nop 1
	v_lshlrev_b64 v[16:17], 6, v[20:21]
	v_lshl_add_u64 v[16:17], s[0:1], 0, v[16:17]
	v_lshl_add_u64 v[16:17], v[16:17], 0, v[146:147]
	global_load_dwordx4 v[16:19], v[16:17], off
	s_waitcnt vmcnt(0)
	v_add_f32_e32 v16, v16, v17
	v_add_f32_e32 v17, v18, v19
	v_add_f32_e32 v16, v16, v17
	v_mov_b32_e32 v17, v16
	s_nop 1
	v_permlane16_swap_b32_e32 v16, v17
	v_add_f32_e32 v16, v16, v17
	v_mov_b32_e32 v17, v16
	s_nop 1
	v_permlane32_swap_b32_e32 v16, v17
	v_add_f32_e32 v16, v16, v17
	v_fmamk_f32 v16, v16, 0x3a800000, v229
	v_cmp_gt_f32_e32 vcc, s55, v16
	v_mul_f32_e32 v17, 0x4b800000, v16
	s_nop 0
	v_cndmask_b32_e32 v16, v16, v17, vcc
	v_rsq_f32_e32 v16, v16
	s_nop 0
	v_mul_f32_e32 v17, 0x45800000, v16
	v_cndmask_b32_e32 v16, v16, v17, vcc
	v_pk_fma_f32 v[12:13], v[12:13], v[16:17], v[60:61] op_sel_hi:[1,0,1]
	v_pk_fma_f32 v[14:15], v[14:15], v[16:17], v[62:63] op_sel_hi:[1,0,1]
	v_pk_fma_f32 v[18:19], v[10:11], v[16:17], v[58:59] op_sel_hi:[1,0,1]
	v_pk_fma_f32 v[10:11], v[8:9], v[16:17], v[56:57] op_sel_hi:[1,0,1]
	v_cvt_pk_bf16_f32 v8, v12, v13
	v_mad_i64_i32 v[12:13], s[0:1], v20, s93, v[138:139]
	v_cvt_pk_bf16_f32 v9, v14, v15
	v_cvt_pk_bf16_f32 v10, v10, v11
	v_cvt_pk_bf16_f32 v11, v18, v19
	v_lshl_add_u64 v[12:13], v[12:13], 0, v[140:141]
	global_store_dwordx4 v[12:13], v[8:11], off
	v_pk_fma_f32 v[6:7], v[6:7], v[16:17], v[50:51] op_sel_hi:[1,0,1]
	v_pk_fma_f32 v[4:5], v[4:5], v[16:17], v[48:49] op_sel_hi:[1,0,1]
	v_pk_fma_f32 v[8:9], v[2:3], v[16:17], v[46:47] op_sel_hi:[1,0,1]
	v_pk_fma_f32 v[2:3], v[0:1], v[16:17], v[44:45] op_sel_hi:[1,0,1]
	v_cvt_pk_bf16_f32 v0, v4, v5
	v_cvt_pk_bf16_f32 v1, v6, v7
	v_cvt_pk_bf16_f32 v2, v2, v3
	v_cvt_pk_bf16_f32 v3, v8, v9
	global_store_dwordx4 v[12:13], v[0:3], off offset:256
	s_waitcnt vmcnt(0)
	s_barrier
	s_waitcnt vmcnt(0)
	s_barrier
	s_and_saveexec_b64 s[0:1], s[26:27]
	s_cbranch_execz .LBB0_901
	s_mov_b64 s[6:7], exec
	v_mbcnt_lo_u32_b32 v0, s6, 0
	v_readlane_b32 s8, v255, 46
	s_cmp_lg_u32 s8, 0
	s_cbranch_scc1 .Lmy_nowb
	buffer_wbl2 sc1
	s_waitcnt vmcnt(0)
.Lmy_nowb:
	s_waitcnt vmcnt(0)
	v_mbcnt_hi_u32_b32 v0, s7, v0
	v_cmp_eq_u32_e32 vcc, 0, v0
	s_and_b64 s[8:9], exec, vcc
	s_mov_b64 exec, s[8:9]
	s_cbranch_execz .LBB0_901
	s_bcnt1_i32_b64 s6, s[6:7]
	v_mov_b32_e32 v0, s6
	global_atomic_add v65, v0, s[70:71] offset:2304
	s_branch .LBB0_901
